# Up epilogue U stores marked sc0 sc1 (write-through) so the grid barrier's L2 writeback has less to flush
# baseline (speedup 1.0000x reference)
;     __device__ __forceinline__ void operator()(const f32x4 (&acc)[2][2][4][2], const pg8::Unit& u, int ui, int wr, int wc, int fr, int fq) const {
;     ...
;             for (int m = 0; m < 4; ++m) {
;                 const int rl = ai * 128 + wr * 64 + m * 16 + fr;
;                 f32x4 a[2], o[2];
; #pragma unroll
;                 for (int n = 0; n < 2; ++n) {
;                     a[n] = acc[ai][0][m][n] * rr[ai][m];
;                     const f32x4 v = acc[ai][1][m][n] * rr[ai][m];
; #pragma unroll
;                     for (int q = 0; q < 2; ++q) {
;                         const int xb = __builtin_bit_cast(int, __builtin_amdgcn_cvt_pkrtz(a[n][2 * q], a[n][2 * q + 1]));
;                         const int t1 = __builtin_amdgcn_mov_dpp(xb, 0x121, 0xf, 0xf, true), t2 = __builtin_amdgcn_mov_dpp(xb, 0x122, 0xf, 0xf, true);
;                         const h2 p1 = __builtin_bit_cast(h2, (fr == 0) ? t1p[n][q] : t1), p2 = __builtin_bit_cast(h2, (fr < 2) ? t2p[n][q] : t2), x2 = __builtin_bit_cast(h2, xb);
;                         t1p[n][q] = t1; t2p[n][q] = t2;
;                         const h2 c = p2 * w0h[n][q] + (p1 * w1h[n][q] + (x2 * w2h[n][q] + bbh[n][q]));
;                         const h2 ea = c * (h2){(_Float16)(-LOG2E), (_Float16)(-LOG2E)};
;                         h2 ex; ex.x = __builtin_exp2f16(ea.x); ex.y = __builtin_exp2f16(ea.y);
;                         const h2 dn = ex + (h2){(_Float16)1.f, (_Float16)1.f};
;                         h2 rc; rc.x = __builtin_amdgcn_rcph(dn.x); rc.y = __builtin_amdgcn_rcph(dn.y);
;                         const h2 sg = c * rc;
;                         o[n][2 * q] = (float)sg.x * v[2 * q]; o[n][2 * q + 1] = (float)sg.y * v[2 * q + 1];
;                     }
;                 }
;                 u32x4 pk; pk.x = cvt_pk_bf16(o[0][0], o[0][1]); pk.y = cvt_pk_bf16(o[0][2], o[0][3]); pk.z = cvt_pk_bf16(o[1][0], o[1][1]); pk.w = cvt_pk_bf16(o[1][2], o[1][3]);
;                 *(u32x4*)(U + (size_t)(u.pm * 256 + rl) * FF + fcol) = pk;
;                 if (ai == 0 && m == 0 && wr == 0 && fr < 2) {
; #pragma unroll
;                     for (int n = 0; n < 2; ++n) { *(f32x4*)(topa + (size_t)(u.pm * 2 + fr) * FF + fcol + 4 * n) = a[n]; *(f32x4*)(topv + (size_t)(u.pm * 2 + fr) * FF + fcol + 4 * n) = acc[0][1][0][n] * rr[0][0]; }
.LBB0_239:
	v_cvt_pk_f16_f32 v225, v146, v147
	v_cvt_pk_f16_f32 v146, v130, v131
	v_cvt_pk_f16_f32 v131, v136, v137
	s_waitcnt lgkmcnt(1)
	v_cvt_pkrtz_f16_f32 v136, v162, v163
	v_cvt_pk_f16_f32 v134, v134, v135
	v_cvt_pk_f16_f32 v135, v138, v139
	v_cvt_pk_f16_f32 v130, v132, v133
	v_cvt_pk_f16_f32 v132, v140, v141
	v_mov_b32_dpp v139, v136 row_ror:1 row_mask:0xf bank_mask:0xf bound_ctrl:1
	v_mov_b32_dpp v140, v136 row_ror:2 row_mask:0xf bank_mask:0xf bound_ctrl:1
	v_cvt_pkrtz_f16_f32 v136, v164, v165
	v_pk_mul_f32 v[126:127], v[126:127], v[204:205] op_sel_hi:[1,0]
	v_cvt_pk_f16_f32 v147, v148, v149
	v_cvt_pk_f16_f32 v148, v152, v153
	v_cvt_pk_f16_f32 v138, v142, v143
	v_mov_b32_dpp v141, v136 row_ror:1 row_mask:0xf bank_mask:0xf bound_ctrl:1
	v_mov_b32_dpp v142, v136 row_ror:2 row_mask:0xf bank_mask:0xf bound_ctrl:1
	s_waitcnt lgkmcnt(0)
	v_cvt_pkrtz_f16_f32 v136, v166, v167
	v_cvt_pkrtz_f16_f32 v152, v126, v127
	v_cvt_pk_f16_f32 v154, v154, v155
	v_cvt_pk_f16_f32 v155, v158, v159
	v_cvt_pk_f16_f32 v133, v144, v145
	v_mov_b32_dpp v143, v136 row_ror:1 row_mask:0xf bank_mask:0xf bound_ctrl:1
	v_mov_b32_dpp v144, v136 row_ror:2 row_mask:0xf bank_mask:0xf bound_ctrl:1
	v_mov_b32_dpp v136, v152 row_ror:1 row_mask:0xf bank_mask:0xf bound_ctrl:1
	v_cvt_pk_f16_f32 v151, v150, v151
	v_mov_b32_dpp v137, v152 row_ror:2 row_mask:0xf bank_mask:0xf bound_ctrl:1
	v_cndmask_b32_e64 v139, v136, v139, s[68:69]
	v_pk_fma_f16 v152, v154, v152, v155
	v_cndmask_b32_e64 v140, v137, v140, s[76:77]
	v_pk_fma_f16 v139, v151, v139, v152
	v_pk_mul_f32 v[128:129], v[128:129], v[204:205] op_sel_hi:[1,0]
	v_pk_fma_f16 v152, v225, v140, v139
	v_cvt_pk_f16_f32 v149, v156, v157
	v_pk_mul_f16 v139, v152, s52 op_sel_hi:[1,0]
	v_cvt_pkrtz_f16_f32 v157, v128, v129
	v_exp_f16_sdwa v139, v139 dst_sel:WORD_1 dst_unused:UNUSED_PRESERVE src0_sel:WORD_1
	s_nop 0
	v_exp_f16_sdwa v139, v139 dst_sel:WORD_0 dst_unused:UNUSED_PRESERVE src0_sel:WORD_0
	v_cvt_pk_f16_f32 v150, v160, v161
	v_pk_mul_f32 v[118:119], v[118:119], v[204:205] op_sel_hi:[1,0]
	v_pk_mul_f32 v[120:121], v[120:121], v[204:205] op_sel_hi:[1,0]
	v_pk_add_f16 v139, v139, 1.0 op_sel_hi:[1,0]
	v_mov_b32_dpp v140, v157 row_ror:2 row_mask:0xf bank_mask:0xf bound_ctrl:1
	v_rcp_f16_e32 v153, v139
	s_nop 0
	v_rcp_f16_sdwa v153, v139 dst_sel:WORD_1 dst_unused:UNUSED_PRESERVE src0_sel:WORD_1
	v_mov_b32_dpp v139, v157 row_ror:1 row_mask:0xf bank_mask:0xf bound_ctrl:1
	v_cndmask_b32_e64 v141, v139, v141, s[68:69]
	v_pk_fma_f16 v157, v149, v157, v150
	v_cndmask_b32_e64 v142, v140, v142, s[76:77]
	v_pk_fma_f16 v141, v148, v141, v157
	v_pk_fma_f16 v141, v147, v142, v141
	v_cvt_pkrtz_f16_f32 v145, v168, v169
	v_pk_mul_f16 v142, v141, s52 op_sel_hi:[1,0]
	v_cvt_pkrtz_f16_f32 v159, v120, v121
	v_exp_f16_sdwa v142, v142 dst_sel:WORD_1 dst_unused:UNUSED_PRESERVE src0_sel:WORD_1
	s_nop 0
	v_exp_f16_sdwa v142, v142 dst_sel:WORD_0 dst_unused:UNUSED_PRESERVE src0_sel:WORD_0
	v_mov_b32_dpp v158, v145 row_ror:1 row_mask:0xf bank_mask:0xf bound_ctrl:1
	v_mov_b32_dpp v145, v145 row_ror:2 row_mask:0xf bank_mask:0xf bound_ctrl:1
	v_pk_mul_f32 v[124:125], v[124:125], v[204:205] op_sel_hi:[1,0]
	v_pk_add_f16 v142, v142, 1.0 op_sel_hi:[1,0]
	v_pk_mul_f16 v153, v152, v153
	v_rcp_f16_sdwa v142, v142 dst_sel:WORD_1 dst_unused:UNUSED_PRESERVE src0_sel:WORD_1
	s_nop 0
	v_rcp_f16_sdwa v142, v142 dst_sel:WORD_0 dst_unused:UNUSED_PRESERVE src0_sel:WORD_0
	v_pk_mul_f32 v[122:123], v[122:123], v[204:205] op_sel_hi:[1,0]
	v_cvt_pkrtz_f16_f32 v156, v118, v119
	v_pk_mul_f16 v157, v141, v142
	v_fma_mix_f32 v152, v153, v122, 0 op_sel_hi:[1,0,0]
	v_fma_mix_f32 v153, v153, v123, 0 op_sel:[1,0,0] op_sel_hi:[1,0,0]
	v_mov_b32_dpp v141, v156 row_ror:1 row_mask:0xf bank_mask:0xf bound_ctrl:1
	v_mov_b32_dpp v142, v156 row_ror:2 row_mask:0xf bank_mask:0xf bound_ctrl:1
	v_cndmask_b32_e64 v143, v141, v143, s[68:69]
	v_pk_fma_f16 v156, v135, v156, v138
	v_cndmask_b32_e64 v144, v142, v144, s[76:77]
	v_pk_fma_f16 v143, v134, v143, v156
	v_pk_fma_f16 v160, v146, v144, v143
	v_pk_mul_f16 v143, v160, s52 op_sel_hi:[1,0]
	v_pk_mul_f32 v[114:115], v[114:115], v[204:205] op_sel_hi:[1,0]
	v_exp_f16_sdwa v143, v143 dst_sel:WORD_1 dst_unused:UNUSED_PRESERVE src0_sel:WORD_1
	s_nop 0
	v_exp_f16_sdwa v143, v143 dst_sel:WORD_0 dst_unused:UNUSED_PRESERVE src0_sel:WORD_0
	v_lshl_add_u32 v224, s40, 8, v206
	v_pk_mul_f32 v[116:117], v[116:117], v[204:205] op_sel_hi:[1,0]
	v_lshl_add_u32 v223, s40, 1, v1
	v_pk_add_f16 v143, v143, 1.0 op_sel_hi:[1,0]
	v_mov_b32_dpp v144, v159 row_ror:2 row_mask:0xf bank_mask:0xf bound_ctrl:1
	v_rcp_f16_e32 v161, v143
	v_rcp_f16_sdwa v162, v143 dst_sel:DWORD dst_unused:UNUSED_PAD src0_sel:WORD_1
	v_mov_b32_dpp v143, v159 row_ror:1 row_mask:0xf bank_mask:0xf bound_ctrl:1
	v_cndmask_b32_e64 v158, v143, v158, s[68:69]
	v_pk_fma_f16 v159, v132, v159, v133
	v_cndmask_b32_e64 v145, v144, v145, s[76:77]
	v_pk_fma_f16 v158, v131, v158, v159
	s_nop 0
	v_pk_fma_f16 v145, v130, v145, v158
	s_nop 0
	v_pk_mul_f16 v158, v145, s52 op_sel_hi:[1,0]
	s_nop 0
	v_exp_f16_e32 v163, v158
	v_exp_f16_sdwa v164, v158 dst_sel:DWORD dst_unused:UNUSED_PAD src0_sel:WORD_1
	v_fma_mix_f32 v158, v157, v124, 0 op_sel_hi:[1,0,0]
	v_fma_mix_f32 v159, v157, v125, 0 op_sel:[1,0,0] op_sel_hi:[1,0,0]
	v_pack_b32_f16 v156, v161, v162
	v_pack_b32_f16 v157, v163, v164
	v_pk_add_f16 v157, v157, 1.0 op_sel_hi:[1,0]
	s_nop 0
	v_rcp_f16_e32 v161, v157
	v_rcp_f16_sdwa v162, v157 dst_sel:DWORD dst_unused:UNUSED_PAD src0_sel:WORD_1
	v_pk_mul_f16 v157, v160, v156
	v_pack_b32_f16 v160, v161, v162
	v_pk_mul_f16 v145, v145, v160
	v_fma_mix_f32 v162, v157, v114, 0 op_sel_hi:[1,0,0]
	v_fma_mix_f32 v163, v157, v115, 0 op_sel:[1,0,0] op_sel_hi:[1,0,0]
	v_cvt_pk_bf16_f32 v156, v152, v153
	v_mov_b64_e32 v[152:153], s[50:51]
	v_mad_i64_i32 v[152:153], s[20:21], v224, s38, v[152:153]
	v_fma_mix_f32 v160, v145, v116, 0 op_sel_hi:[1,0,0]
	v_fma_mix_f32 v161, v145, v117, 0 op_sel:[1,0,0] op_sel_hi:[1,0,0]
	v_cvt_pk_bf16_f32 v157, v158, v159
	v_cvt_pk_bf16_f32 v158, v162, v163
	v_cvt_pk_bf16_f32 v159, v160, v161
	v_lshl_add_u64 v[152:153], v[194:195], 1, v[152:153]
	global_store_dwordx4 v[152:153], v[156:159], off sc0 sc1
	s_and_saveexec_b64 s[20:21], s[18:19]
	s_cbranch_execz .LBB0_241
	s_movk_i32 s12, 0x2c00
	v_mov_b64_e32 v[156:157], s[58:59]
	v_mov_b64_e32 v[152:153], s[94:95]
	v_mad_i64_i32 v[156:157], s[18:19], v223, s12, v[156:157]
	v_mad_i64_i32 v[152:153], s[18:19], v223, s12, v[152:153]
	v_lshl_add_u64 v[156:157], v[156:157], 0, v[202:203]
	v_lshl_add_u64 v[152:153], v[152:153], 0, v[202:203]
	global_store_dwordx4 v[156:157], v[126:129], off sc0 sc1
	global_store_dwordx4 v[152:153], v[122:125], off sc0 sc1
	global_store_dwordx4 v[156:157], v[118:121], off offset:16 sc0 sc1
	global_store_dwordx4 v[152:153], v[114:117], off offset:16 sc0 sc1
; __device__ __forceinline__ unsigned cvt_pk_bf16(float lo, float hi) { const f32x2 v = {lo, hi}; const bf16x2_t b = __builtin_convertvector(v, bf16x2_t); return __builtin_bit_cast(unsigned, b); }
;     __device__ __forceinline__ void operator()(const f32x4 (&acc)[2][2][4][2], const pg8::Unit& u, int ui, int wr, int wc, int fr, int fq) const {
;     ...
;                 for (int n = 0; n < 2; ++n) {
;                     a[n] = acc[ai][0][m][n] * rr[ai][m];
;                     const f32x4 v = acc[ai][1][m][n] * rr[ai][m];
; #pragma unroll
;                     for (int q = 0; q < 2; ++q) {
;                         const int xb = __builtin_bit_cast(int, __builtin_amdgcn_cvt_pkrtz(a[n][2 * q], a[n][2 * q + 1]));
;                         const int t1 = __builtin_amdgcn_mov_dpp(xb, 0x121, 0xf, 0xf, true), t2 = __builtin_amdgcn_mov_dpp(xb, 0x122, 0xf, 0xf, true);
;                         const h2 p1 = __builtin_bit_cast(h2, (fr == 0) ? t1p[n][q] : t1), p2 = __builtin_bit_cast(h2, (fr < 2) ? t2p[n][q] : t2), x2 = __builtin_bit_cast(h2, xb);
;                         t1p[n][q] = t1; t2p[n][q] = t2;
;                         const h2 c = p2 * w0h[n][q] + (p1 * w1h[n][q] + (x2 * w2h[n][q] + bbh[n][q]));
;                         const h2 ea = c * (h2){(_Float16)(-LOG2E), (_Float16)(-LOG2E)};
;                         h2 ex; ex.x = __builtin_exp2f16(ea.x); ex.y = __builtin_exp2f16(ea.y);
;                         const h2 dn = ex + (h2){(_Float16)1.f, (_Float16)1.f};
;                         h2 rc; rc.x = __builtin_amdgcn_rcph(dn.x); rc.y = __builtin_amdgcn_rcph(dn.y);
;                         const h2 sg = c * rc;
;                         o[n][2 * q] = (float)sg.x * v[2 * q]; o[n][2 * q + 1] = (float)sg.y * v[2 * q + 1];
;                     }
;                 }
;                 u32x4 pk; pk.x = cvt_pk_bf16(o[0][0], o[0][1]); pk.y = cvt_pk_bf16(o[0][2], o[0][3]); pk.z = cvt_pk_bf16(o[1][0], o[1][1]); pk.w = cvt_pk_bf16(o[1][2], o[1][3]);
;                 *(u32x4*)(U + (size_t)(u.pm * 256 + rl) * FF + fcol) = pk;
.LBB0_241:
	s_or_b64 exec, exec, s[20:21]
	s_nop 0
	v_mov_b32_e32 v114, v205
	v_pk_mul_f32 v[110:111], v[110:111], v[114:115] op_sel_hi:[1,0]
	v_pk_mul_f32 v[94:95], v[94:95], v[200:201] op_sel_hi:[1,0]
	v_cvt_pkrtz_f16_f32 v110, v110, v111
	v_cvt_pkrtz_f16_f32 v94, v94, v95
	v_pk_mul_f32 v[86:87], v[86:87], v[200:201] op_sel_hi:[1,0]
	v_mov_b32_dpp v115, v110 row_ror:1 row_mask:0xf bank_mask:0xf bound_ctrl:1
	v_mov_b32_dpp v116, v110 row_ror:2 row_mask:0xf bank_mask:0xf bound_ctrl:1
	v_cndmask_b32_e64 v111, v115, v136, s[68:69]
	v_pk_fma_f16 v110, v154, v110, v155
	v_cndmask_b32_e64 v117, v116, v137, s[76:77]
	v_pk_fma_f16 v110, v151, v111, v110
	v_pk_mul_f32 v[102:103], v[102:103], v[114:115] op_sel_hi:[1,0]
	v_pk_fma_f16 v117, v225, v117, v110
	v_cvt_pkrtz_f16_f32 v102, v102, v103
	v_pk_mul_f16 v110, v117, s52 op_sel_hi:[1,0]
	v_pk_mul_f32 v[104:105], v[104:105], v[114:115] op_sel_hi:[1,0]
	v_exp_f16_e32 v118, v110
	v_exp_f16_sdwa v119, v110 dst_sel:DWORD dst_unused:UNUSED_PAD src0_sel:WORD_1
	v_pk_mul_f32 v[110:111], v[112:113], v[114:115] op_sel_hi:[1,0]
	v_cvt_pkrtz_f16_f32 v104, v104, v105
	v_cvt_pkrtz_f16_f32 v110, v110, v111
	v_pack_b32_f16 v112, v118, v119
	v_pk_add_f16 v112, v112, 1.0 op_sel_hi:[1,0]
	v_mov_b32_dpp v118, v110 row_ror:1 row_mask:0xf bank_mask:0xf bound_ctrl:1
	v_mov_b32_dpp v119, v110 row_ror:2 row_mask:0xf bank_mask:0xf bound_ctrl:1
	v_cndmask_b32_e64 v111, v118, v139, s[68:69]
	v_pk_fma_f16 v110, v149, v110, v150
	v_cndmask_b32_e64 v120, v119, v140, s[76:77]
	v_pk_fma_f16 v110, v148, v111, v110
	v_rcp_f16_sdwa v112, v112 dst_sel:WORD_1 dst_unused:UNUSED_PRESERVE src0_sel:WORD_1
	v_pk_fma_f16 v120, v147, v120, v110
	v_rcp_f16_sdwa v112, v112 dst_sel:WORD_0 dst_unused:UNUSED_PRESERVE src0_sel:WORD_0
	v_pk_mul_f16 v110, v120, s52 op_sel_hi:[1,0]
	v_mov_b32_dpp v123, v104 row_ror:2 row_mask:0xf bank_mask:0xf bound_ctrl:1
	v_exp_f16_sdwa v110, v110 dst_sel:WORD_1 dst_unused:UNUSED_PRESERVE src0_sel:WORD_1
	s_nop 0
	v_exp_f16_sdwa v110, v110 dst_sel:WORD_0 dst_unused:UNUSED_PRESERVE src0_sel:WORD_0
	v_cndmask_b32_e64 v124, v123, v144, s[76:77]
	v_pk_mul_f32 v[108:109], v[108:109], v[114:115] op_sel_hi:[1,0]
	v_pk_add_f16 v110, v110, 1.0 op_sel_hi:[1,0]
	v_pk_mul_f16 v111, v117, v112
	v_rcp_f16_e32 v112, v110
	s_nop 0
	v_rcp_f16_sdwa v112, v110 dst_sel:WORD_1 dst_unused:UNUSED_PRESERVE src0_sel:WORD_1
	v_mov_b32_dpp v117, v102 row_ror:2 row_mask:0xf bank_mask:0xf bound_ctrl:1
	v_cvt_f32_f16_e32 v110, v111
	v_cvt_f32_f16_sdwa v111, v111 dst_sel:DWORD dst_unused:UNUSED_PAD src0_sel:WORD_1
	v_mov_b32_dpp v113, v102 row_ror:1 row_mask:0xf bank_mask:0xf bound_ctrl:1
	v_cndmask_b32_e64 v103, v113, v141, s[68:69]
	v_pk_fma_f16 v102, v135, v102, v138
	v_pk_mul_f16 v112, v120, v112
	v_cndmask_b32_e64 v120, v117, v142, s[76:77]
	v_pk_fma_f16 v102, v134, v103, v102
	v_cvt_f32_f16_sdwa v103, v112 dst_sel:DWORD dst_unused:UNUSED_PAD src0_sel:WORD_1
	v_pk_fma_f16 v120, v146, v120, v102
	v_pk_mul_f32 v[106:107], v[106:107], v[114:115] op_sel_hi:[1,0]
	v_pk_mul_f16 v102, v120, s52 op_sel_hi:[1,0]
	v_pk_mul_f32 v[100:101], v[100:101], v[114:115] op_sel_hi:[1,0]
	v_exp_f16_e32 v121, v102
	v_exp_f16_sdwa v122, v102 dst_sel:DWORD dst_unused:UNUSED_PAD src0_sel:WORD_1
	v_cvt_f32_f16_e32 v102, v112
	v_pk_mul_f32 v[98:99], v[98:99], v[114:115] op_sel_hi:[1,0]
	v_cvt_pkrtz_f16_f32 v86, v86, v87
	v_pack_b32_f16 v112, v121, v122
	v_mov_b32_dpp v122, v104 row_ror:1 row_mask:0xf bank_mask:0xf bound_ctrl:1
	v_cndmask_b32_e64 v105, v122, v143, s[68:69]
	v_pk_fma_f16 v104, v132, v104, v133
	v_pk_add_f16 v112, v112, 1.0 op_sel_hi:[1,0]
	v_pk_fma_f16 v104, v131, v105, v104
	v_rcp_f16_e32 v121, v112
	v_pk_fma_f16 v124, v130, v124, v104
	v_rcp_f16_sdwa v112, v112 dst_sel:DWORD dst_unused:UNUSED_PAD src0_sel:WORD_1
	v_pk_mul_f16 v104, v124, s52 op_sel_hi:[1,0]
	v_pk_mul_f32 v[88:89], v[88:89], v[200:201] op_sel_hi:[1,0]
	v_exp_f16_e32 v125, v104
	v_exp_f16_sdwa v126, v104 dst_sel:DWORD dst_unused:UNUSED_PAD src0_sel:WORD_1
	v_pk_mul_f32 v[104:105], v[106:107], v[110:111]
	v_pk_mul_f32 v[106:107], v[108:109], v[102:103]
	v_pack_b32_f16 v102, v121, v112
	v_pack_b32_f16 v103, v125, v126
	v_pk_add_f16 v103, v103, 1.0 op_sel_hi:[1,0]
	v_cvt_pkrtz_f16_f32 v88, v88, v89
	v_rcp_f16_e32 v108, v103
	s_nop 0
	v_rcp_f16_sdwa v108, v103 dst_sel:WORD_1 dst_unused:UNUSED_PRESERVE src0_sel:WORD_1
	v_pk_mul_f16 v103, v120, v102
	v_pk_mul_f32 v[90:91], v[90:91], v[200:201] op_sel_hi:[1,0]
	v_pk_mul_f16 v109, v124, v108
	v_pk_mul_f32 v[92:93], v[92:93], v[200:201] op_sel_hi:[1,0]
	v_fma_mix_f32 v98, v103, v98, 0 op_sel_hi:[1,0,0]
	v_fma_mix_f32 v99, v103, v99, 0 op_sel:[1,0,0] op_sel_hi:[1,0,0]
	v_cvt_pk_bf16_f32 v102, v104, v105
	v_fma_mix_f32 v100, v109, v100, 0 op_sel_hi:[1,0,0]
	v_fma_mix_f32 v101, v109, v101, 0 op_sel:[1,0,0] op_sel_hi:[1,0,0]
	v_mov_b32_dpp v108, v94 row_ror:1 row_mask:0xf bank_mask:0xf bound_ctrl:1
	v_mov_b32_dpp v109, v94 row_ror:2 row_mask:0xf bank_mask:0xf bound_ctrl:1
	v_cndmask_b32_e64 v95, v108, v115, s[68:69]
	v_pk_fma_f16 v94, v154, v94, v155
	v_cndmask_b32_e64 v110, v109, v116, s[76:77]
	v_pk_fma_f16 v94, v151, v95, v94
	v_cvt_pk_bf16_f32 v104, v98, v99
	v_cvt_pk_bf16_f32 v105, v100, v101
	v_or_b32_e32 v100, 16, v224
	v_mov_b64_e32 v[98:99], s[50:51]
	v_pk_fma_f16 v110, v225, v110, v94
	v_cvt_pk_bf16_f32 v103, v106, v107
	v_mad_i64_i32 v[106:107], s[18:19], v100, s38, v[98:99]
	v_lshlrev_b64 v[100:101], 1, v[194:195]
	v_pk_mul_f16 v94, v110, s52 op_sel_hi:[1,0]
	v_pk_mul_f32 v[82:83], v[82:83], v[200:201] op_sel_hi:[1,0]
	v_exp_f16_e32 v111, v94
	v_exp_f16_sdwa v112, v94 dst_sel:DWORD dst_unused:UNUSED_PAD src0_sel:WORD_1
; __device__ __forceinline__ unsigned cvt_pk_bf16(float lo, float hi) { const f32x2 v = {lo, hi}; const bf16x2_t b = __builtin_convertvector(v, bf16x2_t); return __builtin_bit_cast(unsigned, b); }
;     __device__ __forceinline__ void operator()(const f32x4 (&acc)[2][2][4][2], const pg8::Unit& u, int ui, int wr, int wc, int fr, int fq) const {
;     ...
;                 for (int n = 0; n < 2; ++n) {
;                     a[n] = acc[ai][0][m][n] * rr[ai][m];
;                     const f32x4 v = acc[ai][1][m][n] * rr[ai][m];
; #pragma unroll
;                     for (int q = 0; q < 2; ++q) {
;                         const int xb = __builtin_bit_cast(int, __builtin_amdgcn_cvt_pkrtz(a[n][2 * q], a[n][2 * q + 1]));
;                         const int t1 = __builtin_amdgcn_mov_dpp(xb, 0x121, 0xf, 0xf, true), t2 = __builtin_amdgcn_mov_dpp(xb, 0x122, 0xf, 0xf, true);
;                         const h2 p1 = __builtin_bit_cast(h2, (fr == 0) ? t1p[n][q] : t1), p2 = __builtin_bit_cast(h2, (fr < 2) ? t2p[n][q] : t2), x2 = __builtin_bit_cast(h2, xb);
;                         t1p[n][q] = t1; t2p[n][q] = t2;
;                         const h2 c = p2 * w0h[n][q] + (p1 * w1h[n][q] + (x2 * w2h[n][q] + bbh[n][q]));
;                         const h2 ea = c * (h2){(_Float16)(-LOG2E), (_Float16)(-LOG2E)};
;                         h2 ex; ex.x = __builtin_exp2f16(ea.x); ex.y = __builtin_exp2f16(ea.y);
;                         const h2 dn = ex + (h2){(_Float16)1.f, (_Float16)1.f};
;                         h2 rc; rc.x = __builtin_amdgcn_rcph(dn.x); rc.y = __builtin_amdgcn_rcph(dn.y);
;                         const h2 sg = c * rc;
;                         o[n][2 * q] = (float)sg.x * v[2 * q]; o[n][2 * q + 1] = (float)sg.y * v[2 * q + 1];
;                     }
;                 }
;                 u32x4 pk; pk.x = cvt_pk_bf16(o[0][0], o[0][1]); pk.y = cvt_pk_bf16(o[0][2], o[0][3]); pk.z = cvt_pk_bf16(o[1][0], o[1][1]); pk.w = cvt_pk_bf16(o[1][2], o[1][3]);
;                 *(u32x4*)(U + (size_t)(u.pm * 256 + rl) * FF + fcol) = pk;
	v_lshl_add_u64 v[94:95], v[106:107], 0, v[100:101]
	global_store_dwordx4 v[94:95], v[102:105], off sc0 sc1
	v_pk_mul_f32 v[94:95], v[96:97], v[200:201] op_sel_hi:[1,0]
	v_pack_b32_f16 v96, v111, v112
	v_cvt_pkrtz_f16_f32 v94, v94, v95
	v_pk_add_f16 v96, v96, 1.0 op_sel_hi:[1,0]
	v_pk_mul_f32 v[84:85], v[84:85], v[200:201] op_sel_hi:[1,0]
	v_mov_b32_dpp v102, v94 row_ror:1 row_mask:0xf bank_mask:0xf bound_ctrl:1
	v_mov_b32_dpp v103, v94 row_ror:2 row_mask:0xf bank_mask:0xf bound_ctrl:1
	v_cndmask_b32_e64 v95, v102, v118, s[68:69]
	v_pk_fma_f16 v94, v149, v94, v150
	v_cndmask_b32_e64 v104, v103, v119, s[76:77]
	v_pk_fma_f16 v94, v148, v95, v94
	v_rcp_f16_sdwa v96, v96 dst_sel:WORD_1 dst_unused:UNUSED_PRESERVE src0_sel:WORD_1
	v_pk_fma_f16 v104, v147, v104, v94
	v_rcp_f16_sdwa v96, v96 dst_sel:WORD_0 dst_unused:UNUSED_PRESERVE src0_sel:WORD_0
	v_pk_mul_f16 v94, v104, s52 op_sel_hi:[1,0]
	v_pk_mul_f32 v[62:63], v[62:63], v[198:199] op_sel_hi:[1,0]
	v_exp_f16_sdwa v94, v94 dst_sel:WORD_1 dst_unused:UNUSED_PRESERVE src0_sel:WORD_1
	s_nop 0
	v_exp_f16_sdwa v94, v94 dst_sel:WORD_0 dst_unused:UNUSED_PRESERVE src0_sel:WORD_0
	v_cvt_pkrtz_f16_f32 v62, v62, v63
	v_pk_mul_f32 v[54:55], v[54:55], v[198:199] op_sel_hi:[1,0]
	v_pk_add_f16 v94, v94, 1.0 op_sel_hi:[1,0]
	v_pk_mul_f16 v95, v110, v96
	v_rcp_f16_e32 v96, v94
	s_nop 0
	v_rcp_f16_sdwa v96, v94 dst_sel:WORD_1 dst_unused:UNUSED_PRESERVE src0_sel:WORD_1
	v_mov_b32_dpp v110, v88 row_ror:2 row_mask:0xf bank_mask:0xf bound_ctrl:1
	v_cndmask_b32_e64 v111, v110, v123, s[76:77]
	v_cvt_f32_f16_e32 v94, v95
	v_mov_b32_dpp v97, v86 row_ror:1 row_mask:0xf bank_mask:0xf bound_ctrl:1
	v_pk_mul_f16 v96, v104, v96
	v_mov_b32_dpp v104, v86 row_ror:2 row_mask:0xf bank_mask:0xf bound_ctrl:1
	v_cndmask_b32_e64 v87, v97, v113, s[68:69]
	v_pk_fma_f16 v86, v135, v86, v138
	v_cndmask_b32_e64 v105, v104, v117, s[76:77]
	v_pk_fma_f16 v86, v134, v87, v86
	v_cvt_f32_f16_sdwa v87, v96 dst_sel:DWORD dst_unused:UNUSED_PAD src0_sel:WORD_1
	v_pk_fma_f16 v105, v146, v105, v86
	v_cvt_f32_f16_sdwa v95, v95 dst_sel:DWORD dst_unused:UNUSED_PAD src0_sel:WORD_1
	v_pk_mul_f16 v86, v105, s52 op_sel_hi:[1,0]
	v_cvt_pkrtz_f16_f32 v54, v54, v55
	v_exp_f16_e32 v106, v86
	v_exp_f16_sdwa v107, v86 dst_sel:DWORD dst_unused:UNUSED_PAD src0_sel:WORD_1
	v_cvt_f32_f16_e32 v86, v96
	v_pk_mul_f32 v[56:57], v[56:57], v[198:199] op_sel_hi:[1,0]
	v_pk_mul_f32 v[58:59], v[58:59], v[198:199] op_sel_hi:[1,0]
	v_pack_b32_f16 v96, v106, v107
	v_mov_b32_dpp v107, v88 row_ror:1 row_mask:0xf bank_mask:0xf bound_ctrl:1
	v_cndmask_b32_e64 v89, v107, v122, s[68:69]
	v_pk_fma_f16 v88, v132, v88, v133
	v_pk_add_f16 v96, v96, 1.0 op_sel_hi:[1,0]
	v_pk_fma_f16 v88, v131, v89, v88
	v_rcp_f16_e32 v106, v96
	v_pk_fma_f16 v111, v130, v111, v88
	v_rcp_f16_sdwa v96, v96 dst_sel:DWORD dst_unused:UNUSED_PAD src0_sel:WORD_1
	v_pk_mul_f16 v88, v111, s52 op_sel_hi:[1,0]
	v_pk_mul_f32 v[86:87], v[92:93], v[86:87]
	v_exp_f16_e32 v112, v88
	v_exp_f16_sdwa v113, v88 dst_sel:DWORD dst_unused:UNUSED_PAD src0_sel:WORD_1
	v_pk_mul_f32 v[88:89], v[90:91], v[94:95]
	v_pack_b32_f16 v90, v106, v96
	v_cvt_pkrtz_f16_f32 v56, v56, v57
	v_pack_b32_f16 v91, v112, v113
	v_pk_add_f16 v91, v91, 1.0 op_sel_hi:[1,0]
	v_pk_mul_f32 v[60:61], v[60:61], v[198:199] op_sel_hi:[1,0]
	v_rcp_f16_e32 v92, v91
	s_nop 0
	v_rcp_f16_sdwa v92, v91 dst_sel:WORD_1 dst_unused:UNUSED_PRESERVE src0_sel:WORD_1
	v_pk_mul_f16 v91, v105, v90
	v_pk_mul_f32 v[50:51], v[50:51], v[198:199] op_sel_hi:[1,0]
	v_pk_mul_f16 v93, v111, v92
	v_pk_mul_f32 v[52:53], v[52:53], v[198:199] op_sel_hi:[1,0]
	v_fma_mix_f32 v90, v91, v82, 0 op_sel_hi:[1,0,0]
	v_fma_mix_f32 v91, v91, v83, 0 op_sel:[1,0,0] op_sel_hi:[1,0,0]
	v_cvt_pk_bf16_f32 v82, v88, v89
	v_mov_b32_e32 v88, v201
	v_pk_mul_f32 v[78:79], v[78:79], v[88:89] op_sel_hi:[1,0]
	v_cvt_pkrtz_f16_f32 v78, v78, v79
	v_cvt_pk_bf16_f32 v83, v86, v87
	s_nop 0
	v_mov_b32_dpp v79, v78 row_ror:1 row_mask:0xf bank_mask:0xf bound_ctrl:1
	v_mov_b32_dpp v89, v78 row_ror:2 row_mask:0xf bank_mask:0xf bound_ctrl:1
	v_cndmask_b32_e64 v79, v79, v108, s[68:69]
	v_pk_fma_f16 v78, v154, v78, v155
	v_cndmask_b32_e64 v89, v89, v109, s[76:77]
	v_pk_fma_f16 v78, v151, v79, v78
	v_or_b32_e32 v86, 32, v224
	v_pk_fma_f16 v89, v225, v89, v78
	v_fma_mix_f32 v92, v93, v84, 0 op_sel_hi:[1,0,0]
	v_fma_mix_f32 v93, v93, v85, 0 op_sel:[1,0,0] op_sel_hi:[1,0,0]
	v_mad_i64_i32 v[86:87], s[18:19], v86, s38, v[98:99]
	v_pk_mul_f16 v78, v89, s52 op_sel_hi:[1,0]
	v_cvt_pk_bf16_f32 v84, v90, v91
	v_cvt_pk_bf16_f32 v85, v92, v93
	v_exp_f16_e32 v90, v78
	v_exp_f16_sdwa v91, v78 dst_sel:DWORD dst_unused:UNUSED_PAD src0_sel:WORD_1
	v_lshl_add_u64 v[78:79], v[86:87], 0, v[100:101]
	global_store_dwordx4 v[78:79], v[82:85], off sc0 sc1
	v_pk_mul_f32 v[78:79], v[80:81], v[88:89] op_sel_hi:[1,0]
	v_pack_b32_f16 v80, v90, v91
	v_cvt_pkrtz_f16_f32 v78, v78, v79
	v_pk_add_f16 v80, v80, 1.0 op_sel_hi:[1,0]
	v_pk_mul_f32 v[70:71], v[70:71], v[88:89] op_sel_hi:[1,0]
	v_mov_b32_dpp v79, v78 row_ror:1 row_mask:0xf bank_mask:0xf bound_ctrl:1
	v_mov_b32_dpp v82, v78 row_ror:2 row_mask:0xf bank_mask:0xf bound_ctrl:1
	v_cndmask_b32_e64 v79, v79, v102, s[68:69]
	v_pk_fma_f16 v78, v149, v78, v150
	v_cndmask_b32_e64 v82, v82, v103, s[76:77]
	v_pk_fma_f16 v78, v148, v79, v78
	v_rcp_f16_sdwa v80, v80 dst_sel:WORD_1 dst_unused:UNUSED_PRESERVE src0_sel:WORD_1
	v_pk_fma_f16 v82, v147, v82, v78
	v_rcp_f16_sdwa v80, v80 dst_sel:WORD_0 dst_unused:UNUSED_PRESERVE src0_sel:WORD_0
	v_pk_mul_f16 v78, v82, s52 op_sel_hi:[1,0]
	v_cvt_pkrtz_f16_f32 v70, v70, v71
	v_exp_f16_sdwa v78, v78 dst_sel:WORD_1 dst_unused:UNUSED_PRESERVE src0_sel:WORD_1
	s_nop 0
; #define LAS __attribute__((address_space(3)))
;     __device__ __forceinline__ void operator()(const f32x4 (&acc)[2][2][4][2], const pg8::Unit& u, int ui, int wr, int wc, int fr, int fq) const {
;     ...
;         for (int ai = 0; ai < 2; ++ai) {
;             f32x4 pv[2];
;             if (ai == 0 && wr == 0) { pv[0] = (f32x4){0.f, 0.f, 0.f, 0.f}; pv[1] = pv[0]; }
;             else { const int pai = (wr == 1) ? ai : ai - 1, pwr = wr ^ 1; const int xr = (fr >= 14) ? fr - 14 : 0;
; #pragma unroll
;                 for (int n = 0; n < 2; ++n) pv[n] = *(const LAS f32x4*)(xch + ((pai * 2 + pwr) * 4 + wc) * 64 + xr * 32 + 8 * fq + 4 * n); }
;             int t1p[2][2], t2p[2][2];
; #pragma unroll
;             for (int n = 0; n < 2; ++n)
; #pragma unroll
;                 for (int q = 0; q < 2; ++q) { const int pb = __builtin_bit_cast(int, __builtin_amdgcn_cvt_pkrtz(pv[n][2 * q], pv[n][2 * q + 1]));
;                     t1p[n][q] = __builtin_amdgcn_mov_dpp(pb, 0x121, 0xf, 0xf, true); t2p[n][q] = __builtin_amdgcn_mov_dpp(pb, 0x122, 0xf, 0xf, true); }
; #pragma unroll
;             for (int m = 0; m < 4; ++m) {
;                 const int rl = ai * 128 + wr * 64 + m * 16 + fr;
;                 f32x4 a[2], o[2];
; #pragma unroll
;                 for (int n = 0; n < 2; ++n) {
;                     a[n] = acc[ai][0][m][n] * rr[ai][m];
;                     const f32x4 v = acc[ai][1][m][n] * rr[ai][m];
; #pragma unroll
;                     for (int q = 0; q < 2; ++q) {
;                         const int xb = __builtin_bit_cast(int, __builtin_amdgcn_cvt_pkrtz(a[n][2 * q], a[n][2 * q + 1]));
;                         const int t1 = __builtin_amdgcn_mov_dpp(xb, 0x121, 0xf, 0xf, true), t2 = __builtin_amdgcn_mov_dpp(xb, 0x122, 0xf, 0xf, true);
;                         const h2 p1 = __builtin_bit_cast(h2, (fr == 0) ? t1p[n][q] : t1), p2 = __builtin_bit_cast(h2, (fr < 2) ? t2p[n][q] : t2), x2 = __builtin_bit_cast(h2, xb);
;                         t1p[n][q] = t1; t2p[n][q] = t2;
;                         const h2 c = p2 * w0h[n][q] + (p1 * w1h[n][q] + (x2 * w2h[n][q] + bbh[n][q]));
;                         const h2 ea = c * (h2){(_Float16)(-LOG2E), (_Float16)(-LOG2E)};
;                         h2 ex; ex.x = __builtin_exp2f16(ea.x); ex.y = __builtin_exp2f16(ea.y);
;                         const h2 dn = ex + (h2){(_Float16)1.f, (_Float16)1.f};
	v_exp_f16_sdwa v78, v78 dst_sel:WORD_0 dst_unused:UNUSED_PRESERVE src0_sel:WORD_0
	v_mov_b32_dpp v71, v70 row_ror:1 row_mask:0xf bank_mask:0xf bound_ctrl:1
	v_cndmask_b32_e64 v71, v71, v97, s[68:69]
	v_pk_add_f16 v78, v78, 1.0 op_sel_hi:[1,0]
	v_pk_mul_f16 v79, v89, v80
	v_rcp_f16_e32 v80, v78
	s_nop 0
	v_rcp_f16_sdwa v80, v78 dst_sel:WORD_1 dst_unused:UNUSED_PRESERVE src0_sel:WORD_1
	v_pk_mul_f32 v[72:73], v[72:73], v[88:89] op_sel_hi:[1,0]
	v_cvt_f32_f16_e32 v78, v79
	v_cvt_pkrtz_f16_f32 v72, v72, v73
	v_mov_b32_dpp v81, v70 row_ror:2 row_mask:0xf bank_mask:0xf bound_ctrl:1
	v_pk_fma_f16 v70, v135, v70, v138
	v_cndmask_b32_e64 v81, v81, v104, s[76:77]
	v_pk_fma_f16 v70, v134, v71, v70
	v_pk_mul_f16 v80, v82, v80
	v_pk_fma_f16 v81, v146, v81, v70
	v_mov_b32_dpp v73, v72 row_ror:1 row_mask:0xf bank_mask:0xf bound_ctrl:1
	v_pk_mul_f16 v70, v81, s52 op_sel_hi:[1,0]
	v_cvt_f32_f16_sdwa v71, v80 dst_sel:DWORD dst_unused:UNUSED_PAD src0_sel:WORD_1
	v_exp_f16_e32 v82, v70
	v_exp_f16_sdwa v83, v70 dst_sel:DWORD dst_unused:UNUSED_PAD src0_sel:WORD_1
	v_cvt_f32_f16_e32 v70, v80
	v_cndmask_b32_e64 v73, v73, v107, s[68:69]
	v_cvt_f32_f16_sdwa v79, v79 dst_sel:DWORD dst_unused:UNUSED_PAD src0_sel:WORD_1
	v_pack_b32_f16 v80, v82, v83
	v_mov_b32_dpp v83, v72 row_ror:2 row_mask:0xf bank_mask:0xf bound_ctrl:1
	v_pk_fma_f16 v72, v132, v72, v133
	v_cndmask_b32_e64 v83, v83, v110, s[76:77]
	v_pk_fma_f16 v72, v131, v73, v72
	v_pk_mul_f32 v[74:75], v[74:75], v[88:89] op_sel_hi:[1,0]
	v_pk_fma_f16 v83, v130, v83, v72
	v_pk_add_f16 v80, v80, 1.0 op_sel_hi:[1,0]
	v_pk_mul_f16 v72, v83, s52 op_sel_hi:[1,0]
	v_rcp_f16_e32 v82, v80
	v_exp_f16_e32 v84, v72
	v_exp_f16_sdwa v85, v72 dst_sel:DWORD dst_unused:UNUSED_PAD src0_sel:WORD_1
	v_rcp_f16_sdwa v80, v80 dst_sel:DWORD dst_unused:UNUSED_PAD src0_sel:WORD_1
	v_pk_mul_f32 v[72:73], v[74:75], v[78:79]
	v_pk_mul_f32 v[76:77], v[76:77], v[88:89] op_sel_hi:[1,0]
	v_pack_b32_f16 v75, v84, v85
	v_pk_add_f16 v75, v75, 1.0 op_sel_hi:[1,0]
	v_pk_mul_f32 v[70:71], v[76:77], v[70:71]
	v_rcp_f16_e32 v76, v75
	s_nop 0
	v_rcp_f16_sdwa v76, v75 dst_sel:WORD_1 dst_unused:UNUSED_PRESERVE src0_sel:WORD_1
	v_pack_b32_f16 v74, v82, v80
	v_pk_mul_f16 v75, v81, v74
	v_pk_mul_f32 v[66:67], v[66:67], v[88:89] op_sel_hi:[1,0]
	v_pk_mul_f16 v77, v83, v76
	v_pk_mul_f32 v[68:69], v[68:69], v[88:89] op_sel_hi:[1,0]
	v_fma_mix_f32 v74, v75, v66, 0 op_sel_hi:[1,0,0]
	v_fma_mix_f32 v75, v75, v67, 0 op_sel:[1,0,0] op_sel_hi:[1,0,0]
	v_cvt_pk_bf16_f32 v66, v72, v73
	v_cvt_pk_bf16_f32 v67, v70, v71
	ds_read_b128 v[70:73], v220
	v_fma_mix_f32 v76, v77, v68, 0 op_sel_hi:[1,0,0]
	v_fma_mix_f32 v77, v77, v69, 0 op_sel:[1,0,0] op_sel_hi:[1,0,0]
	v_cvt_pk_bf16_f32 v68, v74, v75
	v_or_b32_e32 v74, 48, v224
	v_mad_i64_i32 v[74:75], s[18:19], v74, s38, v[98:99]
	v_cvt_pk_bf16_f32 v69, v76, v77
	v_lshl_add_u64 v[74:75], v[74:75], 0, v[100:101]
	global_store_dwordx4 v[74:75], v[66:69], off sc0 sc1
	ds_read_b128 v[66:69], v220 offset:16
	s_waitcnt lgkmcnt(1)
	v_cvt_pkrtz_f16_f32 v70, v70, v71
	v_mov_b32_dpp v74, v62 row_ror:1 row_mask:0xf bank_mask:0xf bound_ctrl:1
	v_mov_b32_dpp v75, v62 row_ror:2 row_mask:0xf bank_mask:0xf bound_ctrl:1
	v_mov_b32_dpp v71, v70 row_ror:1 row_mask:0xf bank_mask:0xf bound_ctrl:1
	v_mov_b32_dpp v70, v70 row_ror:2 row_mask:0xf bank_mask:0xf bound_ctrl:1
	v_cndmask_b32_e64 v63, v74, v71, s[68:69]
	v_pk_fma_f16 v62, v154, v62, v155
	v_cndmask_b32_e64 v70, v75, v70, s[76:77]
	v_pk_fma_f16 v62, v151, v63, v62
	v_cvt_pkrtz_f16_f32 v72, v72, v73
	v_pk_fma_f16 v70, v225, v70, v62
	s_waitcnt lgkmcnt(0)
	v_cvt_pkrtz_f16_f32 v66, v66, v67
	v_pk_mul_f16 v62, v70, s52 op_sel_hi:[1,0]
	v_mov_b32_dpp v73, v72 row_ror:1 row_mask:0xf bank_mask:0xf bound_ctrl:1
	v_exp_f16_e32 v71, v62
	v_exp_f16_sdwa v76, v62 dst_sel:DWORD dst_unused:UNUSED_PAD src0_sel:WORD_1
	v_pk_mul_f32 v[62:63], v[64:65], v[198:199] op_sel_hi:[1,0]
	v_mov_b32_dpp v72, v72 row_ror:2 row_mask:0xf bank_mask:0xf bound_ctrl:1
	v_cvt_pkrtz_f16_f32 v62, v62, v63
	v_pack_b32_f16 v64, v71, v76
	v_pk_add_f16 v64, v64, 1.0 op_sel_hi:[1,0]
	v_mov_b32_dpp v71, v62 row_ror:1 row_mask:0xf bank_mask:0xf bound_ctrl:1
	v_mov_b32_dpp v76, v62 row_ror:2 row_mask:0xf bank_mask:0xf bound_ctrl:1
	v_cndmask_b32_e64 v63, v71, v73, s[68:69]
	v_pk_fma_f16 v62, v149, v62, v150
	v_cndmask_b32_e64 v72, v76, v72, s[76:77]
	v_pk_fma_f16 v62, v148, v63, v62
	v_rcp_f16_sdwa v64, v64 dst_sel:WORD_1 dst_unused:UNUSED_PRESERVE src0_sel:WORD_1
	v_pk_fma_f16 v72, v147, v72, v62
	v_rcp_f16_sdwa v64, v64 dst_sel:WORD_0 dst_unused:UNUSED_PRESERVE src0_sel:WORD_0
	v_pk_mul_f16 v62, v72, s52 op_sel_hi:[1,0]
	v_mov_b32_dpp v67, v66 row_ror:1 row_mask:0xf bank_mask:0xf bound_ctrl:1
	v_exp_f16_sdwa v62, v62 dst_sel:WORD_1 dst_unused:UNUSED_PRESERVE src0_sel:WORD_1
	s_nop 0
	v_exp_f16_sdwa v62, v62 dst_sel:WORD_0 dst_unused:UNUSED_PRESERVE src0_sel:WORD_0
	v_mov_b32_dpp v66, v66 row_ror:2 row_mask:0xf bank_mask:0xf bound_ctrl:1
	v_cvt_pkrtz_f16_f32 v68, v68, v69
	v_pk_add_f16 v62, v62, 1.0 op_sel_hi:[1,0]
	v_pk_mul_f16 v63, v70, v64
	v_rcp_f16_e32 v64, v62
	s_nop 0
	v_rcp_f16_sdwa v64, v62 dst_sel:WORD_1 dst_unused:UNUSED_PRESERVE src0_sel:WORD_1
	v_mov_b32_dpp v70, v54 row_ror:2 row_mask:0xf bank_mask:0xf bound_ctrl:1
	v_cndmask_b32_e64 v66, v70, v66, s[76:77]
	v_mov_b32_dpp v69, v68 row_ror:1 row_mask:0xf bank_mask:0xf bound_ctrl:1
	v_mov_b32_dpp v65, v54 row_ror:1 row_mask:0xf bank_mask:0xf bound_ctrl:1
	v_cndmask_b32_e64 v55, v65, v67, s[68:69]
	v_pk_fma_f16 v54, v135, v54, v138
	v_pk_mul_f16 v64, v72, v64
	v_pk_fma_f16 v54, v134, v55, v54
	v_cvt_f32_f16_sdwa v55, v64 dst_sel:DWORD dst_unused:UNUSED_PAD src0_sel:WORD_1
; __device__ __forceinline__ unsigned cvt_pk_bf16(float lo, float hi) { const f32x2 v = {lo, hi}; const bf16x2_t b = __builtin_convertvector(v, bf16x2_t); return __builtin_bit_cast(unsigned, b); }
;     __device__ __forceinline__ void operator()(const f32x4 (&acc)[2][2][4][2], const pg8::Unit& u, int ui, int wr, int wc, int fr, int fq) const {
;     ...
;                 for (int n = 0; n < 2; ++n) {
;                     a[n] = acc[ai][0][m][n] * rr[ai][m];
;                     const f32x4 v = acc[ai][1][m][n] * rr[ai][m];
; #pragma unroll
;                     for (int q = 0; q < 2; ++q) {
;                         const int xb = __builtin_bit_cast(int, __builtin_amdgcn_cvt_pkrtz(a[n][2 * q], a[n][2 * q + 1]));
;                         const int t1 = __builtin_amdgcn_mov_dpp(xb, 0x121, 0xf, 0xf, true), t2 = __builtin_amdgcn_mov_dpp(xb, 0x122, 0xf, 0xf, true);
;                         const h2 p1 = __builtin_bit_cast(h2, (fr == 0) ? t1p[n][q] : t1), p2 = __builtin_bit_cast(h2, (fr < 2) ? t2p[n][q] : t2), x2 = __builtin_bit_cast(h2, xb);
;                         t1p[n][q] = t1; t2p[n][q] = t2;
;                         const h2 c = p2 * w0h[n][q] + (p1 * w1h[n][q] + (x2 * w2h[n][q] + bbh[n][q]));
;                         const h2 ea = c * (h2){(_Float16)(-LOG2E), (_Float16)(-LOG2E)};
;                         h2 ex; ex.x = __builtin_exp2f16(ea.x); ex.y = __builtin_exp2f16(ea.y);
;                         const h2 dn = ex + (h2){(_Float16)1.f, (_Float16)1.f};
;                         h2 rc; rc.x = __builtin_amdgcn_rcph(dn.x); rc.y = __builtin_amdgcn_rcph(dn.y);
;                         const h2 sg = c * rc;
;                         o[n][2 * q] = (float)sg.x * v[2 * q]; o[n][2 * q + 1] = (float)sg.y * v[2 * q + 1];
;                     }
;                 }
;                 u32x4 pk; pk.x = cvt_pk_bf16(o[0][0], o[0][1]); pk.y = cvt_pk_bf16(o[0][2], o[0][3]); pk.z = cvt_pk_bf16(o[1][0], o[1][1]); pk.w = cvt_pk_bf16(o[1][2], o[1][3]);
;                 *(u32x4*)(U + (size_t)(u.pm * 256 + rl) * FF + fcol) = pk;
	v_pk_fma_f16 v66, v146, v66, v54
	v_mov_b32_dpp v68, v68 row_ror:2 row_mask:0xf bank_mask:0xf bound_ctrl:1
	v_pk_mul_f16 v54, v66, s52 op_sel_hi:[1,0]
	v_mov_b32_dpp v73, v56 row_ror:2 row_mask:0xf bank_mask:0xf bound_ctrl:1
	v_exp_f16_e32 v67, v54
	v_exp_f16_sdwa v72, v54 dst_sel:DWORD dst_unused:UNUSED_PAD src0_sel:WORD_1
	v_cvt_f32_f16_e32 v54, v64
	v_cndmask_b32_e64 v68, v73, v68, s[76:77]
	v_pack_b32_f16 v64, v67, v72
	v_mov_b32_dpp v72, v56 row_ror:1 row_mask:0xf bank_mask:0xf bound_ctrl:1
	v_cndmask_b32_e64 v57, v72, v69, s[68:69]
	v_pk_fma_f16 v56, v132, v56, v133
	v_pk_fma_f16 v56, v131, v57, v56
	v_pk_add_f16 v64, v64, 1.0 op_sel_hi:[1,0]
	v_pk_fma_f16 v68, v130, v68, v56
	v_rcp_f16_e32 v67, v64
	v_pk_mul_f16 v56, v68, s52 op_sel_hi:[1,0]
	v_rcp_f16_sdwa v64, v64 dst_sel:DWORD dst_unused:UNUSED_PAD src0_sel:WORD_1
	v_exp_f16_e32 v69, v56
	v_exp_f16_sdwa v78, v56 dst_sel:DWORD dst_unused:UNUSED_PAD src0_sel:WORD_1
	v_fma_mix_f32 v56, v63, v58, 0 op_sel_hi:[1,0,0]
	v_fma_mix_f32 v57, v63, v59, 0 op_sel:[1,0,0] op_sel_hi:[1,0,0]
	v_pk_mul_f32 v[54:55], v[60:61], v[54:55]
	v_pack_b32_f16 v58, v67, v64
	v_pack_b32_f16 v59, v69, v78
	v_pk_add_f16 v59, v59, 1.0 op_sel_hi:[1,0]
	v_add_u32_e32 v77, 0x80, v224
	v_rcp_f16_e32 v60, v59
	s_nop 0
	v_rcp_f16_sdwa v60, v59 dst_sel:WORD_1 dst_unused:UNUSED_PRESERVE src0_sel:WORD_1
	v_pk_mul_f16 v59, v66, v58
	v_pk_mul_f32 v[30:31], v[30:31], v[196:197] op_sel_hi:[1,0]
	v_pk_mul_f16 v61, v68, v60
	v_cvt_pkrtz_f16_f32 v30, v30, v31
	v_fma_mix_f32 v58, v59, v50, 0 op_sel_hi:[1,0,0]
	v_fma_mix_f32 v59, v59, v51, 0 op_sel:[1,0,0] op_sel_hi:[1,0,0]
	v_cvt_pk_bf16_f32 v50, v56, v57
	v_mov_b32_e32 v56, v199
	v_pk_mul_f32 v[46:47], v[46:47], v[56:57] op_sel_hi:[1,0]
	v_fma_mix_f32 v60, v61, v52, 0 op_sel_hi:[1,0,0]
	v_fma_mix_f32 v61, v61, v53, 0 op_sel:[1,0,0] op_sel_hi:[1,0,0]
	v_cvt_pkrtz_f16_f32 v46, v46, v47
	v_cvt_pk_bf16_f32 v52, v58, v59
	v_cvt_pk_bf16_f32 v51, v54, v55
	v_mov_b32_dpp v57, v46 row_ror:1 row_mask:0xf bank_mask:0xf bound_ctrl:1
	v_mov_b32_dpp v58, v46 row_ror:2 row_mask:0xf bank_mask:0xf bound_ctrl:1
	v_cndmask_b32_e64 v47, v57, v74, s[68:69]
	v_pk_fma_f16 v46, v154, v46, v155
	v_cndmask_b32_e64 v59, v58, v75, s[76:77]
	v_pk_fma_f16 v46, v151, v47, v46
	v_mad_i64_i32 v[54:55], s[18:19], v77, s38, v[98:99]
	v_pk_fma_f16 v59, v225, v59, v46
	v_cvt_pk_bf16_f32 v53, v60, v61
	v_pk_mul_f16 v46, v59, s52 op_sel_hi:[1,0]
	v_pk_mul_f32 v[38:39], v[38:39], v[56:57] op_sel_hi:[1,0]
	v_exp_f16_e32 v60, v46
	v_exp_f16_sdwa v61, v46 dst_sel:DWORD dst_unused:UNUSED_PAD src0_sel:WORD_1
	v_lshl_add_u64 v[46:47], v[54:55], 0, v[100:101]
	global_store_dwordx4 v[46:47], v[50:53], off sc0 sc1
	v_pk_mul_f32 v[46:47], v[48:49], v[56:57] op_sel_hi:[1,0]
	v_pack_b32_f16 v48, v60, v61
	v_cvt_pkrtz_f16_f32 v46, v46, v47
	v_pk_add_f16 v48, v48, 1.0 op_sel_hi:[1,0]
	v_cvt_pkrtz_f16_f32 v38, v38, v39
	v_mov_b32_dpp v50, v46 row_ror:1 row_mask:0xf bank_mask:0xf bound_ctrl:1
	v_mov_b32_dpp v51, v46 row_ror:2 row_mask:0xf bank_mask:0xf bound_ctrl:1
	v_cndmask_b32_e64 v47, v50, v71, s[68:69]
	v_pk_fma_f16 v46, v149, v46, v150
	v_cndmask_b32_e64 v52, v51, v76, s[76:77]
	v_pk_fma_f16 v46, v148, v47, v46
	v_rcp_f16_sdwa v48, v48 dst_sel:WORD_1 dst_unused:UNUSED_PRESERVE src0_sel:WORD_1
	v_pk_fma_f16 v52, v147, v52, v46
	v_rcp_f16_sdwa v48, v48 dst_sel:WORD_0 dst_unused:UNUSED_PRESERVE src0_sel:WORD_0
	v_pk_mul_f16 v46, v52, s52 op_sel_hi:[1,0]
	v_pk_mul_f32 v[40:41], v[40:41], v[56:57] op_sel_hi:[1,0]
	v_exp_f16_sdwa v46, v46 dst_sel:WORD_1 dst_unused:UNUSED_PRESERVE src0_sel:WORD_1
	s_nop 0
	v_exp_f16_sdwa v46, v46 dst_sel:WORD_0 dst_unused:UNUSED_PRESERVE src0_sel:WORD_0
	v_cvt_pkrtz_f16_f32 v40, v40, v41
	v_pk_mul_f32 v[42:43], v[42:43], v[56:57] op_sel_hi:[1,0]
	v_pk_add_f16 v46, v46, 1.0 op_sel_hi:[1,0]
	v_pk_mul_f16 v47, v59, v48
	v_rcp_f16_e32 v48, v46
	s_nop 0
	v_rcp_f16_sdwa v48, v46 dst_sel:WORD_1 dst_unused:UNUSED_PRESERVE src0_sel:WORD_1
	v_mov_b32_dpp v59, v40 row_ror:2 row_mask:0xf bank_mask:0xf bound_ctrl:1
	v_cndmask_b32_e64 v60, v59, v73, s[76:77]
	v_cvt_f32_f16_e32 v46, v47
	v_mov_b32_dpp v49, v38 row_ror:1 row_mask:0xf bank_mask:0xf bound_ctrl:1
	v_pk_mul_f16 v48, v52, v48
	v_mov_b32_dpp v52, v38 row_ror:2 row_mask:0xf bank_mask:0xf bound_ctrl:1
	v_cndmask_b32_e64 v39, v49, v65, s[68:69]
	v_pk_fma_f16 v38, v135, v38, v138
	v_cndmask_b32_e64 v53, v52, v70, s[76:77]
	v_pk_fma_f16 v38, v134, v39, v38
	v_cvt_f32_f16_sdwa v39, v48 dst_sel:DWORD dst_unused:UNUSED_PAD src0_sel:WORD_1
	v_pk_fma_f16 v53, v146, v53, v38
	v_cvt_f32_f16_sdwa v47, v47 dst_sel:DWORD dst_unused:UNUSED_PAD src0_sel:WORD_1
	v_pk_mul_f16 v38, v53, s52 op_sel_hi:[1,0]
	v_pk_mul_f32 v[44:45], v[44:45], v[56:57] op_sel_hi:[1,0]
	v_exp_f16_e32 v54, v38
	v_exp_f16_sdwa v55, v38 dst_sel:DWORD dst_unused:UNUSED_PAD src0_sel:WORD_1
	v_cvt_f32_f16_e32 v38, v48
	v_pk_mul_f32 v[34:35], v[34:35], v[56:57] op_sel_hi:[1,0]
	v_pk_mul_f32 v[36:37], v[36:37], v[56:57] op_sel_hi:[1,0]
	v_pack_b32_f16 v48, v54, v55
	v_mov_b32_dpp v55, v40 row_ror:1 row_mask:0xf bank_mask:0xf bound_ctrl:1
	v_cndmask_b32_e64 v41, v55, v72, s[68:69]
	v_pk_fma_f16 v40, v132, v40, v133
	v_pk_add_f16 v48, v48, 1.0 op_sel_hi:[1,0]
	v_pk_fma_f16 v40, v131, v41, v40
	v_rcp_f16_e32 v54, v48
	v_pk_fma_f16 v60, v130, v60, v40
	v_rcp_f16_sdwa v48, v48 dst_sel:DWORD dst_unused:UNUSED_PAD src0_sel:WORD_1
	v_pk_mul_f16 v40, v60, s52 op_sel_hi:[1,0]
	v_pk_mul_f32 v[38:39], v[44:45], v[38:39]
	v_exp_f16_e32 v61, v40
	v_exp_f16_sdwa v62, v40 dst_sel:DWORD dst_unused:UNUSED_PAD src0_sel:WORD_1
	v_pk_mul_f32 v[40:41], v[42:43], v[46:47]
	v_pack_b32_f16 v42, v54, v48
; __device__ __forceinline__ unsigned cvt_pk_bf16(float lo, float hi) { const f32x2 v = {lo, hi}; const bf16x2_t b = __builtin_convertvector(v, bf16x2_t); return __builtin_bit_cast(unsigned, b); }
;     __device__ __forceinline__ void operator()(const f32x4 (&acc)[2][2][4][2], const pg8::Unit& u, int ui, int wr, int wc, int fr, int fq) const {
;     ...
;                 for (int n = 0; n < 2; ++n) {
;                     a[n] = acc[ai][0][m][n] * rr[ai][m];
;                     const f32x4 v = acc[ai][1][m][n] * rr[ai][m];
; #pragma unroll
;                     for (int q = 0; q < 2; ++q) {
;                         const int xb = __builtin_bit_cast(int, __builtin_amdgcn_cvt_pkrtz(a[n][2 * q], a[n][2 * q + 1]));
;                         const int t1 = __builtin_amdgcn_mov_dpp(xb, 0x121, 0xf, 0xf, true), t2 = __builtin_amdgcn_mov_dpp(xb, 0x122, 0xf, 0xf, true);
;                         const h2 p1 = __builtin_bit_cast(h2, (fr == 0) ? t1p[n][q] : t1), p2 = __builtin_bit_cast(h2, (fr < 2) ? t2p[n][q] : t2), x2 = __builtin_bit_cast(h2, xb);
;                         t1p[n][q] = t1; t2p[n][q] = t2;
;                         const h2 c = p2 * w0h[n][q] + (p1 * w1h[n][q] + (x2 * w2h[n][q] + bbh[n][q]));
;                         const h2 ea = c * (h2){(_Float16)(-LOG2E), (_Float16)(-LOG2E)};
;                         h2 ex; ex.x = __builtin_exp2f16(ea.x); ex.y = __builtin_exp2f16(ea.y);
;                         const h2 dn = ex + (h2){(_Float16)1.f, (_Float16)1.f};
;                         h2 rc; rc.x = __builtin_amdgcn_rcph(dn.x); rc.y = __builtin_amdgcn_rcph(dn.y);
;                         const h2 sg = c * rc;
;                         o[n][2 * q] = (float)sg.x * v[2 * q]; o[n][2 * q + 1] = (float)sg.y * v[2 * q + 1];
;                     }
;                 }
;                 u32x4 pk; pk.x = cvt_pk_bf16(o[0][0], o[0][1]); pk.y = cvt_pk_bf16(o[0][2], o[0][3]); pk.z = cvt_pk_bf16(o[1][0], o[1][1]); pk.w = cvt_pk_bf16(o[1][2], o[1][3]);
;                 *(u32x4*)(U + (size_t)(u.pm * 256 + rl) * FF + fcol) = pk;
	v_pk_mul_f32 v[22:23], v[22:23], v[196:197] op_sel_hi:[1,0]
	v_pack_b32_f16 v43, v61, v62
	v_pk_add_f16 v43, v43, 1.0 op_sel_hi:[1,0]
	v_cvt_pkrtz_f16_f32 v22, v22, v23
	v_rcp_f16_e32 v44, v43
	s_nop 0
	v_rcp_f16_sdwa v44, v43 dst_sel:WORD_1 dst_unused:UNUSED_PRESERVE src0_sel:WORD_1
	v_pk_mul_f16 v43, v53, v42
	v_pk_mul_f32 v[24:25], v[24:25], v[196:197] op_sel_hi:[1,0]
	v_pk_mul_f16 v45, v60, v44
	v_cvt_pkrtz_f16_f32 v24, v24, v25
	v_fma_mix_f32 v42, v43, v34, 0 op_sel_hi:[1,0,0]
	v_fma_mix_f32 v43, v43, v35, 0 op_sel:[1,0,0] op_sel_hi:[1,0,0]
	v_cvt_pk_bf16_f32 v34, v40, v41
	v_mov_b32_dpp v40, v30 row_ror:1 row_mask:0xf bank_mask:0xf bound_ctrl:1
	v_mov_b32_dpp v41, v30 row_ror:2 row_mask:0xf bank_mask:0xf bound_ctrl:1
	v_cndmask_b32_e64 v31, v40, v57, s[68:69]
	v_pk_fma_f16 v30, v154, v30, v155
	v_fma_mix_f32 v44, v45, v36, 0 op_sel_hi:[1,0,0]
	v_fma_mix_f32 v45, v45, v37, 0 op_sel:[1,0,0] op_sel_hi:[1,0,0]
	v_cvt_pk_bf16_f32 v36, v42, v43
	v_cndmask_b32_e64 v42, v41, v58, s[76:77]
	v_pk_fma_f16 v30, v151, v31, v30
	v_cvt_pk_bf16_f32 v35, v38, v39
	v_add_u32_e32 v38, 0x90, v224
	v_pk_fma_f16 v42, v225, v42, v30
	v_mad_i64_i32 v[38:39], s[18:19], v38, s38, v[98:99]
	v_pk_mul_f16 v30, v42, s52 op_sel_hi:[1,0]
	v_cvt_pk_bf16_f32 v37, v44, v45
	v_exp_f16_e32 v43, v30
	v_exp_f16_sdwa v44, v30 dst_sel:DWORD dst_unused:UNUSED_PAD src0_sel:WORD_1
	v_lshl_add_u64 v[30:31], v[38:39], 0, v[100:101]
	global_store_dwordx4 v[30:31], v[34:37], off sc0 sc1
	v_pk_mul_f32 v[30:31], v[32:33], v[196:197] op_sel_hi:[1,0]
	v_pack_b32_f16 v32, v43, v44
	v_cvt_pkrtz_f16_f32 v30, v30, v31
	v_pk_add_f16 v32, v32, 1.0 op_sel_hi:[1,0]
	v_pk_mul_f32 v[26:27], v[26:27], v[196:197] op_sel_hi:[1,0]
	v_mov_b32_dpp v34, v30 row_ror:1 row_mask:0xf bank_mask:0xf bound_ctrl:1
	v_mov_b32_dpp v35, v30 row_ror:2 row_mask:0xf bank_mask:0xf bound_ctrl:1
	v_cndmask_b32_e64 v31, v34, v50, s[68:69]
	v_pk_fma_f16 v30, v149, v30, v150
	v_cndmask_b32_e64 v36, v35, v51, s[76:77]
	v_pk_fma_f16 v30, v148, v31, v30
	v_rcp_f16_sdwa v32, v32 dst_sel:WORD_1 dst_unused:UNUSED_PRESERVE src0_sel:WORD_1
	v_pk_fma_f16 v36, v147, v36, v30
	v_rcp_f16_sdwa v32, v32 dst_sel:WORD_0 dst_unused:UNUSED_PRESERVE src0_sel:WORD_0
	v_pk_mul_f16 v30, v36, s52 op_sel_hi:[1,0]
	v_pk_mul_f32 v[28:29], v[28:29], v[196:197] op_sel_hi:[1,0]
	v_exp_f16_sdwa v30, v30 dst_sel:WORD_1 dst_unused:UNUSED_PRESERVE src0_sel:WORD_1
	s_nop 0
	v_exp_f16_sdwa v30, v30 dst_sel:WORD_0 dst_unused:UNUSED_PRESERVE src0_sel:WORD_0
	v_pk_mul_f32 v[18:19], v[18:19], v[196:197] op_sel_hi:[1,0]
	v_pk_mul_f32 v[20:21], v[20:21], v[196:197] op_sel_hi:[1,0]
	v_pk_add_f16 v30, v30, 1.0 op_sel_hi:[1,0]
	v_pk_mul_f16 v31, v42, v32
	v_rcp_f16_e32 v32, v30
	s_nop 0
	v_rcp_f16_sdwa v32, v30 dst_sel:WORD_1 dst_unused:UNUSED_PRESERVE src0_sel:WORD_1
	v_mov_b32_dpp v42, v24 row_ror:2 row_mask:0xf bank_mask:0xf bound_ctrl:1
	v_cndmask_b32_e64 v43, v42, v59, s[76:77]
	v_cvt_f32_f16_e32 v30, v31
	v_mov_b32_dpp v33, v22 row_ror:1 row_mask:0xf bank_mask:0xf bound_ctrl:1
	v_pk_mul_f16 v32, v36, v32
	v_mov_b32_dpp v36, v22 row_ror:2 row_mask:0xf bank_mask:0xf bound_ctrl:1
	v_cndmask_b32_e64 v23, v33, v49, s[68:69]
	v_pk_fma_f16 v22, v135, v22, v138
	v_cndmask_b32_e64 v37, v36, v52, s[76:77]
	v_pk_fma_f16 v22, v134, v23, v22
	v_cvt_f32_f16_sdwa v23, v32 dst_sel:DWORD dst_unused:UNUSED_PAD src0_sel:WORD_1
	v_pk_fma_f16 v37, v146, v37, v22
	v_cvt_f32_f16_sdwa v31, v31 dst_sel:DWORD dst_unused:UNUSED_PAD src0_sel:WORD_1
	v_pk_mul_f16 v22, v37, s52 op_sel_hi:[1,0]
	s_nop 0
	v_exp_f16_e32 v38, v22
	v_exp_f16_sdwa v39, v22 dst_sel:DWORD dst_unused:UNUSED_PAD src0_sel:WORD_1
	v_cvt_f32_f16_e32 v22, v32
	v_pack_b32_f16 v32, v38, v39
	v_mov_b32_dpp v39, v24 row_ror:1 row_mask:0xf bank_mask:0xf bound_ctrl:1
	v_cndmask_b32_e64 v25, v39, v55, s[68:69]
	v_pk_fma_f16 v24, v132, v24, v133
	v_pk_add_f16 v32, v32, 1.0 op_sel_hi:[1,0]
	v_pk_fma_f16 v24, v131, v25, v24
	v_rcp_f16_e32 v38, v32
	v_pk_fma_f16 v43, v130, v43, v24
	v_rcp_f16_sdwa v32, v32 dst_sel:DWORD dst_unused:UNUSED_PAD src0_sel:WORD_1
	v_pk_mul_f16 v24, v43, s52 op_sel_hi:[1,0]
	v_pk_mul_f32 v[22:23], v[28:29], v[22:23]
	v_exp_f16_e32 v44, v24
	v_exp_f16_sdwa v45, v24 dst_sel:DWORD dst_unused:UNUSED_PAD src0_sel:WORD_1
	v_pk_mul_f32 v[24:25], v[26:27], v[30:31]
	v_pack_b32_f16 v26, v38, v32
	v_pack_b32_f16 v27, v44, v45
	v_pk_add_f16 v27, v27, 1.0 op_sel_hi:[1,0]
	s_nop 0
	v_rcp_f16_e32 v28, v27
	s_nop 0
	v_rcp_f16_sdwa v28, v27 dst_sel:WORD_1 dst_unused:UNUSED_PRESERVE src0_sel:WORD_1
	v_pk_mul_f16 v27, v37, v26
	v_pk_mul_f16 v29, v43, v28
	v_fma_mix_f32 v26, v27, v18, 0 op_sel_hi:[1,0,0]
	v_fma_mix_f32 v27, v27, v19, 0 op_sel:[1,0,0] op_sel_hi:[1,0,0]
	v_cvt_pk_bf16_f32 v18, v24, v25
	v_mov_b32_e32 v24, v197
	v_pk_mul_f32 v[14:15], v[14:15], v[24:25] op_sel_hi:[1,0]
	v_fma_mix_f32 v28, v29, v20, 0 op_sel_hi:[1,0,0]
;     __device__ __forceinline__ void operator()(const f32x4 (&acc)[2][2][4][2], const pg8::Unit& u, int ui, int wr, int wc, int fr, int fq) const {
;     ...
;                 for (int n = 0; n < 2; ++n) {
;                     a[n] = acc[ai][0][m][n] * rr[ai][m];
;                     const f32x4 v = acc[ai][1][m][n] * rr[ai][m];
; #pragma unroll
;                     for (int q = 0; q < 2; ++q) {
;                         const int xb = __builtin_bit_cast(int, __builtin_amdgcn_cvt_pkrtz(a[n][2 * q], a[n][2 * q + 1]));
;                         const int t1 = __builtin_amdgcn_mov_dpp(xb, 0x121, 0xf, 0xf, true), t2 = __builtin_amdgcn_mov_dpp(xb, 0x122, 0xf, 0xf, true);
;                         const h2 p1 = __builtin_bit_cast(h2, (fr == 0) ? t1p[n][q] : t1), p2 = __builtin_bit_cast(h2, (fr < 2) ? t2p[n][q] : t2), x2 = __builtin_bit_cast(h2, xb);
;                         t1p[n][q] = t1; t2p[n][q] = t2;
;                         const h2 c = p2 * w0h[n][q] + (p1 * w1h[n][q] + (x2 * w2h[n][q] + bbh[n][q]));
;                         const h2 ea = c * (h2){(_Float16)(-LOG2E), (_Float16)(-LOG2E)};
;                         h2 ex; ex.x = __builtin_exp2f16(ea.x); ex.y = __builtin_exp2f16(ea.y);
;                         const h2 dn = ex + (h2){(_Float16)1.f, (_Float16)1.f};
;                         h2 rc; rc.x = __builtin_amdgcn_rcph(dn.x); rc.y = __builtin_amdgcn_rcph(dn.y);
;                         const h2 sg = c * rc;
;                         o[n][2 * q] = (float)sg.x * v[2 * q]; o[n][2 * q + 1] = (float)sg.y * v[2 * q + 1];
;                     }
;                 }
;                 u32x4 pk; pk.x = cvt_pk_bf16(o[0][0], o[0][1]); pk.y = cvt_pk_bf16(o[0][2], o[0][3]); pk.z = cvt_pk_bf16(o[1][0], o[1][1]); pk.w = cvt_pk_bf16(o[1][2], o[1][3]);
;                 *(u32x4*)(U + (size_t)(u.pm * 256 + rl) * FF + fcol) = pk;
;                 if (ai == 0 && m == 0 && wr == 0 && fr < 2) {
; #pragma unroll
;                     for (int n = 0; n < 2; ++n) { *(f32x4*)(topa + (size_t)(u.pm * 2 + fr) * FF + fcol + 4 * n) = a[n]; *(f32x4*)(topv + (size_t)(u.pm * 2 + fr) * FF + fcol + 4 * n) = acc[0][1][0][n] * rr[0][0]; }
;                 }
;                 if (ai == 1 && m == 3 && wr == 1 && fr >= 14) {
; #pragma unroll
;                     for (int n = 0; n < 2; ++n) *(f32x4*)(bot + (size_t)(u.pm * 2 + fr - 14) * FF + fcol + 4 * n) = a[n];
;                 }
	v_fma_mix_f32 v29, v29, v21, 0 op_sel:[1,0,0] op_sel_hi:[1,0,0]
	v_cvt_pkrtz_f16_f32 v25, v14, v15
	v_cvt_pk_bf16_f32 v20, v26, v27
	v_cvt_pk_bf16_f32 v19, v22, v23
	v_mov_b32_dpp v26, v25 row_ror:1 row_mask:0xf bank_mask:0xf bound_ctrl:1
	v_mov_b32_dpp v27, v25 row_ror:2 row_mask:0xf bank_mask:0xf bound_ctrl:1
	v_cndmask_b32_e64 v26, v26, v40, s[68:69]
	v_pk_fma_f16 v25, v154, v25, v155
	v_add_u32_e32 v22, 0xa0, v224
	v_cndmask_b32_e64 v27, v27, v41, s[76:77]
	v_pk_fma_f16 v25, v151, v26, v25
	v_mad_i64_i32 v[22:23], s[18:19], v22, s38, v[98:99]
	v_pk_fma_f16 v25, v225, v27, v25
	v_cvt_pk_bf16_f32 v21, v28, v29
	v_pk_mul_f16 v26, v25, s52 op_sel_hi:[1,0]
	v_lshl_add_u64 v[22:23], v[22:23], 0, v[100:101]
	v_pk_mul_f32 v[16:17], v[16:17], v[24:25] op_sel_hi:[1,0]
	v_exp_f16_e32 v27, v26
	v_exp_f16_sdwa v26, v26 dst_sel:DWORD dst_unused:UNUSED_PAD src0_sel:WORD_1
	global_store_dwordx4 v[22:23], v[18:21], off sc0 sc1
	v_pk_mul_f32 v[6:7], v[6:7], v[24:25] op_sel_hi:[1,0]
	v_pk_mul_f32 v[12:13], v[12:13], v[24:25] op_sel_hi:[1,0]
	v_cvt_pkrtz_f16_f32 v20, v16, v17
	v_pack_b32_f16 v18, v27, v26
	v_pk_add_f16 v18, v18, 1.0 op_sel_hi:[1,0]
	v_mov_b32_dpp v21, v20 row_ror:1 row_mask:0xf bank_mask:0xf bound_ctrl:1
	v_mov_b32_dpp v22, v20 row_ror:2 row_mask:0xf bank_mask:0xf bound_ctrl:1
	v_cndmask_b32_e64 v21, v21, v34, s[68:69]
	v_pk_fma_f16 v20, v149, v20, v150
	v_cndmask_b32_e64 v22, v22, v35, s[76:77]
	v_pk_fma_f16 v20, v148, v21, v20
	v_rcp_f16_sdwa v18, v18 dst_sel:WORD_1 dst_unused:UNUSED_PRESERVE src0_sel:WORD_1
	v_pk_fma_f16 v20, v147, v22, v20
	v_rcp_f16_sdwa v18, v18 dst_sel:WORD_0 dst_unused:UNUSED_PRESERVE src0_sel:WORD_0
	v_pk_mul_f16 v21, v20, s52 op_sel_hi:[1,0]
	v_pk_mul_f32 v[10:11], v[10:11], v[24:25] op_sel_hi:[1,0]
	v_exp_f16_e32 v19, v21
	s_nop 0
	v_exp_f16_sdwa v19, v21 dst_sel:WORD_1 dst_unused:UNUSED_PRESERVE src0_sel:WORD_1
	s_nop 0
	v_pk_add_f16 v19, v19, 1.0 op_sel_hi:[1,0]
	s_nop 0
	v_rcp_f16_e32 v21, v19
	s_nop 0
	v_rcp_f16_sdwa v21, v19 dst_sel:WORD_1 dst_unused:UNUSED_PRESERVE src0_sel:WORD_1
	v_pk_mul_f16 v19, v25, v18
	v_pk_mul_f16 v21, v20, v21
	v_cvt_pkrtz_f16_f32 v20, v6, v7
	s_nop 1
	v_mov_b32_dpp v22, v20 row_ror:1 row_mask:0xf bank_mask:0xf bound_ctrl:1
	v_mov_b32_dpp v23, v20 row_ror:2 row_mask:0xf bank_mask:0xf bound_ctrl:1
	v_cndmask_b32_e64 v22, v22, v33, s[68:69]
	v_pk_fma_f16 v20, v135, v20, v138
	v_cndmask_b32_e64 v23, v23, v36, s[76:77]
	v_pk_fma_f16 v20, v134, v22, v20
	v_fma_mix_f32 v10, v19, v10, 0 op_sel_hi:[1,0,0]
	v_fma_mix_f32 v11, v19, v11, 0 op_sel:[1,0,0] op_sel_hi:[1,0,0]
	v_pk_fma_f16 v22, v146, v23, v20
	s_nop 0
	v_pk_mul_f16 v20, v22, s52 op_sel_hi:[1,0]
	s_nop 0
	v_exp_f16_sdwa v25, v20 dst_sel:DWORD dst_unused:UNUSED_PAD src0_sel:WORD_1
	v_exp_f16_e32 v23, v20
	v_pk_mul_f32 v[8:9], v[8:9], v[24:25] op_sel_hi:[1,0]
	v_pack_b32_f16 v23, v23, v25
	v_cvt_pkrtz_f16_f32 v26, v8, v9
	v_pk_add_f16 v23, v23, 1.0 op_sel_hi:[1,0]
	v_fma_mix_f32 v12, v21, v12, 0 op_sel_hi:[1,0,0]
	v_fma_mix_f32 v13, v21, v13, 0 op_sel:[1,0,0] op_sel_hi:[1,0,0]
	v_mov_b32_dpp v27, v26 row_ror:1 row_mask:0xf bank_mask:0xf bound_ctrl:1
	v_mov_b32_dpp v28, v26 row_ror:2 row_mask:0xf bank_mask:0xf bound_ctrl:1
	v_cndmask_b32_e64 v27, v27, v39, s[68:69]
	v_pk_fma_f16 v26, v132, v26, v133
	v_cndmask_b32_e64 v28, v28, v42, s[76:77]
	v_pk_fma_f16 v26, v131, v27, v26
	v_rcp_f16_e32 v25, v23
	v_pk_fma_f16 v26, v130, v28, v26
	v_rcp_f16_sdwa v23, v23 dst_sel:DWORD dst_unused:UNUSED_PAD src0_sel:WORD_1
	v_pk_mul_f16 v27, v26, s52 op_sel_hi:[1,0]
	v_pk_mul_f32 v[2:3], v[2:3], v[24:25] op_sel_hi:[1,0]
	v_exp_f16_e32 v19, v27
	s_nop 0
	v_exp_f16_sdwa v19, v27 dst_sel:WORD_1 dst_unused:UNUSED_PRESERVE src0_sel:WORD_1
	v_pack_b32_f16 v18, v25, v23
	v_pk_mul_f32 v[4:5], v[4:5], v[24:25] op_sel_hi:[1,0]
	v_pk_add_f16 v19, v19, 1.0 op_sel_hi:[1,0]
	s_nop 0
	v_rcp_f16_e32 v20, v19
	s_nop 0
	v_rcp_f16_sdwa v20, v19 dst_sel:WORD_1 dst_unused:UNUSED_PRESERVE src0_sel:WORD_1
	v_pk_mul_f16 v19, v22, v18
	v_pk_mul_f16 v21, v26, v20
	v_fma_mix_f32 v18, v19, v2, 0 op_sel_hi:[1,0,0]
	v_fma_mix_f32 v19, v19, v3, 0 op_sel:[1,0,0] op_sel_hi:[1,0,0]
	v_cvt_pk_bf16_f32 v2, v10, v11
	v_add_u32_e32 v10, 0xb0, v224
	v_mad_i64_i32 v[10:11], s[18:19], v10, s38, v[98:99]
	v_fma_mix_f32 v20, v21, v4, 0 op_sel_hi:[1,0,0]
	v_fma_mix_f32 v21, v21, v5, 0 op_sel:[1,0,0] op_sel_hi:[1,0,0]
	v_cvt_pk_bf16_f32 v3, v12, v13
	v_cvt_pk_bf16_f32 v4, v18, v19
	v_cvt_pk_bf16_f32 v5, v20, v21
	v_lshl_add_u64 v[10:11], v[10:11], 0, v[100:101]
	global_store_dwordx4 v[10:11], v[2:5], off sc0 sc1
	s_and_saveexec_b64 s[18:19], s[78:79]
	s_cbranch_execz .LBB0_243
	v_add_u32_e32 v4, -14, v223
	v_mov_b64_e32 v[2:3], s[64:65]
	s_movk_i32 s12, 0x2c00
	v_mad_i64_i32 v[2:3], s[20:21], v4, s12, v[2:3]
	v_lshl_add_u64 v[2:3], v[194:195], 2, v[2:3]
	global_store_dwordx4 v[2:3], v[14:17], off sc0 sc1
	global_store_dwordx4 v[2:3], v[6:9], off offset:16 sc0 sc1
